# MLA unit prologue hand-merged: K(1..3)/PE(1..3)/V(1) tiles loaded in the first batch, stored before the first barrier; no extra preheader barrier
# speedup vs baseline: 1.0252x; 1.0032x over previous
; #define LOADK(t) do { const int kp_ = TILE_KPOS(t); kreg = *(const u32x4*)((const char*)P.K + (size_t)(koff + (unsigned)(kp_ * KPITCH * 2))); if (VAR == 0 && tid < 256) pereg = *(const u32x4*)((const char*)P.KPE + (size_t)(peoff + (unsigned)(kp_ * 64))); } while (0)
; #define LOADV(t) do { const int kp_ = TILE_KPOS(t); vreg = *(const u32x4*)((const char*)P.VT + (size_t)(voff + (unsigned)(kp_ * 2))); } while (0)
; #define STOREK(buf) do { LAS unsigned char* kb_ = lds + (buf) * ABUF; *(LAS u32x4*)(kb_ + (tid >> 3) * KP + (tid & 7) * 16) = kreg; \
;         if (VAR == 0 && tid < 256) *(LAS u32x4*)(kb_ + (tid >> 2) * KP + 128 + (tid & 3) * 16) = pereg; } while (0)
; #define STOREV(buf) do { *(LAS u32x4*)(lds + (buf) * ABUF + KT_BYTES + (tid >> 3) * VP + (tid & 7) * 16) = vreg; } while (0)
; template <int VAR>
; __device__ __forceinline__ void attn_phase(LAS unsigned char* lds, const AttnP P, int vcu, int G, int wave_s) {
;     ...
;         const int rot = (VAR == 0 && !isctx) ? ((vcu & 31) * 4 + (vcu >> 5)) % 132 : 0;
;         int na_rs = 0; if (VAR == 2) { na_rs = p_b - 4; na_rs = na_rs < 0 ? 0 : (na_rs > 120 ? 120 : na_rs); }
;         LOADK(0); LOADV(0); STOREK(0); STOREV(0);
;         if (nt > 1) { LOADK(1); STOREK(1); }
;         __syncthreads();
.LBB0_1169:
	s_or_b64 exec, exec, s[0:1]
	s_lshl_b32 s0, s11, 10
	s_or_b32 s0, s0, s8
	v_add_u32_e32 v1, s0, v157
	s_movk_i32 s0, 0x2100
	v_mul_lo_u32 v2, v1, s0
	v_or_b32_e32 v2, v2, v156
	s_lshl_b32 s0, s12, 7
	v_lshl_add_u32 v2, v2, 1, s0
	global_load_dwordx4 v[8:11], v2, s[56:57]
	s_movk_i32 s0, 0x4200
	v_mul_lo_u32 v168, v1, s0
	v_add_u32_e32 v168, v168, v171
	v_add_u32_e32 v168, 0xffffff80, v168
	s_add_i32 s11, s10, 1
	s_cmp_ge_i32 s11, s9
	s_cselect_b32 s1, s9, 0
	s_sub_i32 s11, s11, s1
	s_cmp_ge_i32 s11, s9
	s_cselect_b32 s1, s9, 0
	s_sub_i32 s11, s11, s1
	s_add_i32 s13, s10, 2
	s_cmp_ge_i32 s13, s9
	s_cselect_b32 s1, s9, 0
	s_sub_i32 s13, s13, s1
	s_cmp_ge_i32 s13, s9
	s_cselect_b32 s1, s9, 0
	s_sub_i32 s13, s13, s1
	s_add_i32 s19, s10, 3
	s_cmp_ge_i32 s19, s9
	s_cselect_b32 s1, s9, 0
	s_sub_i32 s19, s19, s1
	s_cmp_ge_i32 s19, s9
	s_cselect_b32 s1, s9, 0
	s_sub_i32 s19, s19, s1
	v_lshl_add_u32 v222, s11, 17, v178
	global_load_dwordx4 v[182:185], v222, s[52:53]
	v_lshl_add_u32 v222, s13, 17, v178
	global_load_dwordx4 v[190:193], v222, s[52:53]
	v_lshl_add_u32 v222, s19, 17, v178
	global_load_dwordx4 v[206:209], v222, s[52:53]
	v_lshl_add_u32 v222, s11, 7, v168
	global_load_dwordx4 v[198:201], v222, s[56:57]
	s_and_saveexec_b64 s[0:1], s[2:3]
	s_cbranch_execz .Lmla_first_nope
	v_lshl_add_u32 v222, s11, 12, v179
	global_load_dwordx4 v[186:189], v222, s[62:63]
	v_lshl_add_u32 v222, s13, 12, v179
	global_load_dwordx4 v[194:197], v222, s[62:63]
	v_lshl_add_u32 v222, s19, 12, v179
	global_load_dwordx4 v[210:213], v222, s[62:63]
.Lmla_first_nope:
	s_or_b64 exec, exec, s[0:1]
	s_waitcnt vmcnt(0)
	ds_write_b128 v172, v[4:7]
	ds_write_b128 v173, v[8:11] offset:13312
	ds_write_b128 v172, v[182:185] offset:22528
	ds_write_b128 v172, v[190:193] offset:45056
	ds_write_b128 v172, v[206:209] offset:58368
	ds_write_b128 v173, v[198:201] offset:35840
	s_and_saveexec_b64 s[0:1], s[2:3]
	ds_write_b128 v176, v[138:141] offset:128
	ds_write_b128 v176, v[186:189] offset:22656
	ds_write_b128 v176, v[194:197] offset:45184
	ds_write_b128 v176, v[210:213] offset:58496
	s_or_b64 exec, exec, s[0:1]
	s_waitcnt lgkmcnt(0)
	s_barrier
	s_add_i32 s19, s10, 4
	s_cmp_ge_i32 s19, s9
	s_cselect_b32 s1, s9, 0
	s_sub_i32 s19, s19, s1
	s_cmp_ge_i32 s19, s9
	s_cselect_b32 s1, s9, 0
	s_sub_i32 s19, s19, s1
	s_add_i32 s13, s10, 2
	s_cmp_ge_i32 s13, s9
	s_cselect_b32 s1, s9, 0
	s_sub_i32 s13, s13, s1
	s_cmp_ge_i32 s13, s9
	s_cselect_b32 s1, s9, 0
	s_sub_i32 s13, s13, s1
	s_and_saveexec_b64 s[0:1], s[2:3]
	s_cbranch_execz .Lmla_pre0
	v_lshl_add_u32 v222, s19, 12, v179
	global_load_dwordx4 v[138:141], v222, s[62:63]

; #define LOADK(t) do { const int kp_ = TILE_KPOS(t); kreg = *(const u32x4*)((const char*)P.K + (size_t)(koff + (unsigned)(kp_ * KPITCH * 2))); if (VAR == 0 && tid < 256) pereg = *(const u32x4*)((const char*)P.KPE + (size_t)(peoff + (unsigned)(kp_ * 64))); } while (0)
; #define LOADV(t) do { const int kp_ = TILE_KPOS(t); vreg = *(const u32x4*)((const char*)P.VT + (size_t)(voff + (unsigned)(kp_ * 2))); } while (0)
; #define STOREK(buf) do { LAS unsigned char* kb_ = lds + (buf) * ABUF; *(LAS u32x4*)(kb_ + (tid >> 3) * KP + (tid & 7) * 16) = kreg; \
;         if (VAR == 0 && tid < 256) *(LAS u32x4*)(kb_ + (tid >> 2) * KP + 128 + (tid & 3) * 16) = pereg; } while (0)
; #define STOREV(buf) do { *(LAS u32x4*)(lds + (buf) * ABUF + KT_BYTES + (tid >> 3) * VP + (tid & 7) * 16) = vreg; } while (0)
; template <int VAR>
; __device__ __forceinline__ void attn_phase(LAS unsigned char* lds, const AttnP P, int vcu, int G, int wave_s) {
;     ...
;         LOADK(0); LOADV(0); STOREK(0); STOREV(0);
;         if (nt > 1) { LOADK(1); STOREK(1); }
;         __syncthreads();
;         f32x16 pc0, pc1; const f32x16 zero16 = {};
;         QK_TILE(pc0, pc1, 0, zero16);
;         float mref = rowmax32(pc0, pc1), lrun = 0.f;
;         if (VAR == 1) { const float sk = P.sink[hq] * LOG2E; mref = __builtin_fmaxf(mref, sk); lrun = (hi == 0) ? __builtin_amdgcn_exp2f(sk - mref) : 0.f; }
;         f32x16 negm = {};
;         if (USE_NEGM) {
; #pragma unroll
;             for (int r = 0; r < 16; ++r) { pc0[r] -= mref; pc1[r] -= mref; negm[r] = -mref; }
;         }
;         float rmc = 0.f;
;         bool need_c = true;
;         __syncthreads();
;         for (int t = 0; t < nt; ++t) {
;             const bool hn = (t + 1 < nt);
;             if (hn) { const int t2 = (t + 2 < nt) ? t + 2 : nt - 1; LOADK(t2); LOADV(t + 1); }
.Lmla_pre1:
	s_or_b64 exec, exec, s[0:1]
	v_lshl_add_u32 v222, s19, 17, v178
	global_load_dwordx4 v[150:153], v222, s[52:53]
	v_lshl_add_u32 v222, s13, 7, v168
	global_load_dwordx4 v[202:205], v222, s[56:57]
	s_add_i32 s20, s10, 4
	s_cmp_ge_i32 s20, s9
	s_cselect_b32 s1, s9, 0
	s_sub_i32 s20, s20, s1
	s_cmp_ge_i32 s20, s9
	s_cselect_b32 s1, s9, 0
	s_sub_i32 s20, s20, s1
	ds_read_b128 v[2:5], v174
	ds_read_b128 v[6:9], v174 offset:32
	s_waitcnt lgkmcnt(1)
	v_mfma_f32_32x32x16_bf16 v[34:49], v[2:5], v[114:117], 0
	ds_read_b128 v[2:5], v174 offset:6656
	ds_read_b128 v[10:13], v174 offset:6688
	v_readlane_b32 s36, v255, 18
	s_mov_b32 s0, s36
	v_readlane_b32 s37, v255, 19
	v_readlane_b32 s38, v255, 20
	v_readlane_b32 s39, v255, 21
	v_readlane_b32 s40, v255, 22
	s_waitcnt lgkmcnt(2)
	v_mfma_f32_32x32x16_bf16 v[34:49], v[6:9], v[118:121], v[34:49]
	v_readlane_b32 s41, v255, 23
	v_readlane_b32 s42, v255, 24
	v_readlane_b32 s43, v255, 25
	v_readlane_b32 s44, v255, 26
	v_readlane_b32 s45, v255, 27
	v_readlane_b32 s46, v255, 28
	v_readlane_b32 s47, v255, 29
	s_waitcnt lgkmcnt(1)
	v_mfma_f32_32x32x16_bf16 v[18:33], v[2:5], v[114:117], 0
	ds_read_b128 v[2:5], v174 offset:64
	ds_read_b128 v[6:9], v174 offset:96
	v_readlane_b32 s48, v255, 30
	v_readlane_b32 s49, v255, 31
	v_readlane_b32 s50, v255, 32
	v_readlane_b32 s51, v255, 33
	v_writelane_b32 v255, s0, 18
	s_mov_b32 s37, s36
	s_waitcnt lgkmcnt(1)
	v_mfma_f32_32x32x16_bf16 v[34:49], v[2:5], v[122:125], v[34:49]
	v_writelane_b32 v255, s1, 19
	v_writelane_b32 v255, s2, 20
	v_writelane_b32 v255, s3, 21
	v_writelane_b32 v255, s4, 22
	v_writelane_b32 v255, s5, 23
	v_writelane_b32 v255, s6, 24
	v_writelane_b32 v255, s7, 25
	v_mfma_f32_32x32x16_bf16 v[18:33], v[10:13], v[118:121], v[18:33]
	ds_read_b128 v[2:5], v174 offset:6720
	ds_read_b128 v[10:13], v174 offset:6752
	v_writelane_b32 v255, s8, 26
	v_writelane_b32 v255, s9, 27
	v_writelane_b32 v255, s10, 28
	v_writelane_b32 v255, s11, 29
	v_writelane_b32 v255, s12, 30
	v_writelane_b32 v255, s13, 31
	s_waitcnt lgkmcnt(2)
	v_mfma_f32_32x32x16_bf16 v[34:49], v[6:9], v[126:129], v[34:49]
	v_writelane_b32 v255, s14, 32
	s_mov_b32 s38, s36
	s_mov_b32 s39, s36
	s_mov_b32 s40, s36
	s_mov_b32 s41, s36
	s_mov_b32 s42, s36
	s_mov_b32 s43, s36
	s_waitcnt lgkmcnt(1)
	v_mfma_f32_32x32x16_bf16 v[18:33], v[2:5], v[122:125], v[18:33]
	ds_read_b128 v[2:5], v174 offset:128
	ds_read_b128 v[6:9], v174 offset:160
	ds_read_b128 v[50:53], v174 offset:6816
	s_mov_b32 s44, s36
	s_mov_b32 s45, s36
	s_mov_b32 s46, s36
	s_mov_b32 s47, s36
	s_mov_b32 s48, s36
	s_waitcnt lgkmcnt(2)
	v_mfma_f32_32x32x16_bf16 v[34:49], v[2:5], v[130:133], v[34:49]
	ds_read_b128 v[2:5], v174 offset:6784
	s_mov_b32 s49, s36
	s_mov_b32 s50, s36
	s_mov_b32 s51, s36
	v_writelane_b32 v255, s15, 33
	s_movk_i32 s0, 0x4200
	v_mul_lo_u32 v1, v1, s0
	v_mfma_f32_32x32x16_bf16 v[18:33], v[10:13], v[126:129], v[18:33]
	v_or_b32_e32 v1, v171, v1
	s_add_i32 s12, s9, -1
	v_lshl_add_u32 v181, s10, 7, v1
	v_mov_b32_e32 v1, 0
	s_mov_b32 s11, 1
	v_mov_b32_e32 v82, 0
	s_waitcnt lgkmcnt(0)
	v_mfma_f32_32x32x16_bf16 v[18:33], v[2:5], v[130:133], v[18:33]
	s_barrier
	v_mfma_f32_32x32x16_bf16 v[34:49], v[6:9], v[134:137], v[34:49]
	v_mov_b64_e32 v[2:3], s[36:37]
	v_mov_b64_e32 v[16:17], s[50:51]
	v_mov_b64_e32 v[4:5], s[38:39]
	v_mov_b64_e32 v[6:7], s[40:41]
	v_mov_b64_e32 v[8:9], s[42:43]
	v_mov_b64_e32 v[10:11], s[44:45]
	v_mov_b64_e32 v[12:13], s[46:47]
	v_mfma_f32_32x32x16_bf16 v[18:33], v[50:53], v[134:137], v[18:33]
	s_nop 3
	v_max_f32_e32 v54, v35, v35
	v_max_f32_e32 v55, v34, v34
	v_max_f32_e32 v54, v55, v54
	v_mov_b64_e32 v[14:15], s[48:49]
	s_nop 3
	v_max3_f32 v50, v36, v37, v19
	v_max3_f32 v51, v54, v18, v20
	v_max3_f32 v51, v51, v21, v38
	v_max3_f32 v50, v50, v40, v41
	v_max3_f32 v51, v51, v39, v22
	v_max3_f32 v50, v50, v24, v25
	v_max3_f32 v51, v51, v23, v42
	v_max3_f32 v50, v50, v44, v45
	v_max3_f32 v51, v51, v43, v26
	v_max3_f32 v50, v50, v28, v29
	v_max3_f32 v51, v51, v27, v46
	v_max3_f32 v50, v50, v48, v49
	v_max3_f32 v51, v51, v47, v30
	v_max3_f32 v50, v50, v32, v33
	v_max3_f32 v50, v51, v31, v50
	v_mov_b32_e32 v51, v50
	s_nop 1
	v_permlane32_swap_b32_e32 v50, v51
	v_max_f32_e32 v51, v51, v51
	v_max_f32_e32 v50, v50, v50
	v_max_f32_e32 v180, v50, v51
	v_xor_b32_e32 v66, 0x80000000, v180
	v_sub_f32_e32 v65, v33, v180
	v_sub_f32_e32 v64, v32, v180
	v_sub_f32_e32 v63, v31, v180
	v_sub_f32_e32 v62, v30, v180
	v_sub_f32_e32 v61, v29, v180
	v_sub_f32_e32 v60, v28, v180
	v_sub_f32_e32 v59, v27, v180
	v_sub_f32_e32 v58, v26, v180
	v_sub_f32_e32 v57, v25, v180
	v_sub_f32_e32 v56, v24, v180
	v_sub_f32_e32 v55, v23, v180
	v_sub_f32_e32 v54, v22, v180
	v_sub_f32_e32 v53, v21, v180
	v_sub_f32_e32 v52, v20, v180
	v_sub_f32_e32 v51, v19, v180
	v_sub_f32_e32 v50, v18, v180
	v_mov_b64_e32 v[32:33], v[16:17]
	v_sub_f32_e32 v49, v49, v180
	v_sub_f32_e32 v48, v48, v180
	v_sub_f32_e32 v47, v47, v180
	v_sub_f32_e32 v46, v46, v180
	v_sub_f32_e32 v45, v45, v180
	v_sub_f32_e32 v44, v44, v180
	v_sub_f32_e32 v43, v43, v180
	v_sub_f32_e32 v42, v42, v180
	v_sub_f32_e32 v41, v41, v180
	v_sub_f32_e32 v40, v40, v180
	v_sub_f32_e32 v39, v39, v180
	v_sub_f32_e32 v38, v38, v180
	v_sub_f32_e32 v37, v37, v180
	v_sub_f32_e32 v36, v36, v180
	v_sub_f32_e32 v35, v35, v180
	v_sub_f32_e32 v34, v34, v180
	v_mov_b64_e32 v[30:31], v[14:15]
	v_mov_b64_e32 v[28:29], v[12:13]
	v_mov_b64_e32 v[26:27], v[10:11]
	v_mov_b64_e32 v[24:25], v[8:9]
	v_mov_b64_e32 v[22:23], v[6:7]
	v_mov_b64_e32 v[20:21], v[4:5]
	v_mov_b64_e32 v[18:19], v[2:3]
	v_mov_b32_e32 v67, v66
	v_mov_b32_e32 v68, v66
	v_mov_b32_e32 v69, v66
	v_mov_b32_e32 v70, v66
	v_mov_b32_e32 v71, v66
	v_mov_b32_e32 v72, v66
	v_mov_b32_e32 v73, v66
	v_mov_b32_e32 v74, v66
	v_mov_b32_e32 v75, v66
	v_mov_b32_e32 v76, v66
	v_mov_b32_e32 v77, v66
	v_mov_b32_e32 v78, v66
	v_mov_b32_e32 v79, v66
	v_mov_b32_e32 v80, v66
	v_mov_b32_e32 v81, v66
	v_add_u32_e32 v228, v166, v165
	v_mov_b32_e32 v167, v82
	v_add_u32_e32 v229, 0xb000, v174
	v_add_u32_e32 v181, 0xb000, v228
	s_and_b64 vcc, exec, s[2:3]
	s_cbranch_vccnz .Lmla_noprio
	s_setprio 1
.Lmla_noprio:
	ds_read_b128 v[182:185], v174 offset:22528
	ds_read_b128 v[186:189], v174 offset:29184
	ds_read_b128 v[190:193], v174 offset:22560
	ds_read_b128 v[194:197], v174 offset:29216
	v_cmp_lt_f32_e32 vcc, s66, v167
